# attention Q loads marked nt (on v37)
# speedup vs baseline: 1.0012x; 1.0012x over previous
; __device__ __forceinline__ float bf2f(unsigned h) { return __uint_as_float(h << 16); }
; __device__ __forceinline__ void mla_unit(char* lds, const bf16_t* __restrict__ Qp, const bf16_t* __restrict__ Knp, const bf16_t* __restrict__ Vp, ...
;     ...
;   const bf16_t* Qw = Qp + (long)(wid * QBLK + r32) * LDQ + hi * 8;
; #pragma unroll
;   for (int d0 = 0; d0 < 8; ++d0) { const u32x4 raw = *reinterpret_cast<const u32x4*>(Qw + d0 * 16); u32x4 w;
; #pragma unroll
;     for (int p = 0; p < 4; ++p) w[p] = cvtpk(bf2f(raw[p] & 0xffffu) * C, bf2f(raw[p] >> 16) * C);
;     qr[d0] = *reinterpret_cast<bf16x8*>(&w); }
.LBB0_238:
	s_lshl_b32 s1, s74, 8
	s_lshl_b64 s[64:65], s[6:7], 13
	s_and_b32 s1, s1, 0x1f00
	s_or_b32 s64, s64, s1
	s_mul_hi_u32 s6, s64, 0x1800
	s_mul_i32 s7, s65, 0x1800
	s_mul_i32 s5, s64, 0x1800
	s_add_i32 s6, s6, s7
	v_readlane_b32 s7, v254, 60
	s_add_u32 s5, s7, s5
	v_readlane_b32 s7, v254, 61
	s_addc_u32 s7, s7, s6
	s_mul_i32 s6, s38, 0x180
	s_add_u32 s6, s5, s6
	s_addc_u32 s7, s7, 0
	v_and_b32_e32 v196, 31, v50
	s_lshl_b32 s39, s8, 5
	v_or_b32_e32 v1, s39, v196
	v_mov_b64_e32 v[2:3], s[6:7]
	s_movk_i32 s5, 0x1800
	v_mad_i64_i32 v[2:3], s[6:7], v1, s5, v[2:3]
	v_lshlrev_b32_e32 v194, 4, v49
	v_mov_b32_e32 v195, v0
	v_lshl_add_u64 v[2:3], v[2:3], 0, v[194:195]
	global_load_dwordx4 v[130:133], v[2:3], off nt
	global_load_dwordx4 v[134:137], v[2:3], off offset:32 nt
	global_load_dwordx4 v[138:141], v[2:3], off offset:64 nt
	global_load_dwordx4 v[142:145], v[2:3], off offset:96 nt
	global_load_dwordx4 v[154:157], v[2:3], off offset:128 nt
	global_load_dwordx4 v[150:153], v[2:3], off offset:160 nt
	global_load_dwordx4 v[146:149], v[2:3], off offset:192 nt
	global_load_dwordx4 v[158:161], v[2:3], off offset:224 nt
	global_load_dwordx4 v[162:165], v[2:3], off offset:256 nt
	global_load_dwordx4 v[166:169], v[2:3], off offset:288 nt
	global_load_dwordx4 v[170:173], v[2:3], off offset:320 nt
	global_load_dwordx4 v[174:177], v[2:3], off offset:352 nt
	s_mov_b32 s6, 0x3dd53b94
	v_lshlrev_b32_e32 v204, 8, v196
	v_and_b32_e32 v51, 0xf0, v48
	v_add_u32_e32 v66, 0, v204
	s_waitcnt vmcnt(20)
	v_xad_u32 v56, v194, v51, v66
	v_lshlrev_b32_e32 v205, 7, v196
	s_and_b32 s0, s0, 0x3fffffc0
	s_lshl_b32 s0, s0, 2
	s_add_i32 s33, s0, 0
	s_add_i32 s33, s33, 0x1e000
	v_lshl_add_u32 v200, v196, 2, s33
	s_waitcnt vmcnt(11)
	v_lshlrev_b32_e32 v1, 16, v130
	v_and_b32_e32 v4, 0xffff0000, v130
	v_lshlrev_b32_e32 v8, 16, v131
	v_and_b32_e32 v5, 0xffff0000, v131
	v_lshlrev_b32_e32 v9, 16, v132
	v_and_b32_e32 v6, 0xffff0000, v132
	v_lshlrev_b32_e32 v10, 16, v133
	v_and_b32_e32 v7, 0xffff0000, v133
	v_mul_f32_e32 v4, 0x3dd53b94, v4
	v_mul_f32_e32 v5, 0x3dd53b94, v5
	v_mul_f32_e32 v6, 0x3dd53b94, v6
	v_mul_f32_e32 v7, 0x3dd53b94, v7
	v_mul_f32_e32 v1, 0x3dd53b94, v1
	v_mul_f32_e32 v8, 0x3dd53b94, v8
	v_mul_f32_e32 v9, 0x3dd53b94, v9
	v_mul_f32_e32 v10, 0x3dd53b94, v10
	v_cvt_pk_bf16_f32 v130, v1, v4
	v_cvt_pk_bf16_f32 v131, v8, v5
	v_cvt_pk_bf16_f32 v132, v9, v6
	v_cvt_pk_bf16_f32 v133, v10, v7
	s_waitcnt vmcnt(10)
	v_lshlrev_b32_e32 v1, 16, v134
	v_and_b32_e32 v4, 0xffff0000, v134
	v_lshlrev_b32_e32 v8, 16, v135
	v_and_b32_e32 v5, 0xffff0000, v135
	v_lshlrev_b32_e32 v9, 16, v136
	v_and_b32_e32 v6, 0xffff0000, v136
	v_lshlrev_b32_e32 v10, 16, v137
	v_and_b32_e32 v7, 0xffff0000, v137
	v_mul_f32_e32 v4, 0x3dd53b94, v4
	v_mul_f32_e32 v5, 0x3dd53b94, v5
	v_mul_f32_e32 v6, 0x3dd53b94, v6
	v_mul_f32_e32 v7, 0x3dd53b94, v7
	v_mul_f32_e32 v1, 0x3dd53b94, v1
	v_mul_f32_e32 v8, 0x3dd53b94, v8
	v_mul_f32_e32 v9, 0x3dd53b94, v9
	v_mul_f32_e32 v10, 0x3dd53b94, v10
	v_cvt_pk_bf16_f32 v134, v1, v4
	v_cvt_pk_bf16_f32 v135, v8, v5
	v_cvt_pk_bf16_f32 v136, v9, v6
	v_cvt_pk_bf16_f32 v137, v10, v7
	s_waitcnt vmcnt(9)
	v_lshlrev_b32_e32 v1, 16, v138
	v_and_b32_e32 v4, 0xffff0000, v138
	v_lshlrev_b32_e32 v8, 16, v139
	v_and_b32_e32 v5, 0xffff0000, v139
	v_lshlrev_b32_e32 v9, 16, v140
	v_and_b32_e32 v6, 0xffff0000, v140
	v_lshlrev_b32_e32 v10, 16, v141
	v_and_b32_e32 v7, 0xffff0000, v141
	v_mul_f32_e32 v4, 0x3dd53b94, v4
	v_mul_f32_e32 v5, 0x3dd53b94, v5
	v_mul_f32_e32 v6, 0x3dd53b94, v6
	v_mul_f32_e32 v7, 0x3dd53b94, v7
	v_mul_f32_e32 v1, 0x3dd53b94, v1
	v_mul_f32_e32 v8, 0x3dd53b94, v8
	v_mul_f32_e32 v9, 0x3dd53b94, v9
	v_mul_f32_e32 v10, 0x3dd53b94, v10
	v_cvt_pk_bf16_f32 v138, v1, v4
	v_cvt_pk_bf16_f32 v139, v8, v5
	v_cvt_pk_bf16_f32 v140, v9, v6
	v_cvt_pk_bf16_f32 v141, v10, v7
	s_waitcnt vmcnt(8)
	v_lshlrev_b32_e32 v1, 16, v142
	v_and_b32_e32 v4, 0xffff0000, v142
	v_lshlrev_b32_e32 v8, 16, v143
	v_and_b32_e32 v5, 0xffff0000, v143
	v_lshlrev_b32_e32 v9, 16, v144
	v_and_b32_e32 v6, 0xffff0000, v144
	v_lshlrev_b32_e32 v10, 16, v145
	v_and_b32_e32 v7, 0xffff0000, v145
	v_mul_f32_e32 v4, 0x3dd53b94, v4
	v_mul_f32_e32 v5, 0x3dd53b94, v5
	v_mul_f32_e32 v6, 0x3dd53b94, v6
	v_mul_f32_e32 v7, 0x3dd53b94, v7
	v_mul_f32_e32 v1, 0x3dd53b94, v1
	v_mul_f32_e32 v8, 0x3dd53b94, v8
	v_mul_f32_e32 v9, 0x3dd53b94, v9
	v_mul_f32_e32 v10, 0x3dd53b94, v10
	v_cvt_pk_bf16_f32 v142, v1, v4
	v_cvt_pk_bf16_f32 v143, v8, v5
	v_cvt_pk_bf16_f32 v144, v9, v6
	v_cvt_pk_bf16_f32 v145, v10, v7
	s_waitcnt vmcnt(7)
	v_lshlrev_b32_e32 v1, 16, v154
	v_and_b32_e32 v4, 0xffff0000, v154
	v_lshlrev_b32_e32 v8, 16, v155
	v_and_b32_e32 v5, 0xffff0000, v155
	v_lshlrev_b32_e32 v9, 16, v156
	v_and_b32_e32 v6, 0xffff0000, v156
	v_lshlrev_b32_e32 v10, 16, v157
	v_and_b32_e32 v7, 0xffff0000, v157
	v_mul_f32_e32 v4, 0x3dd53b94, v4
	v_mul_f32_e32 v5, 0x3dd53b94, v5
	v_mul_f32_e32 v6, 0x3dd53b94, v6
	v_mul_f32_e32 v7, 0x3dd53b94, v7
	v_mul_f32_e32 v1, 0x3dd53b94, v1
	v_mul_f32_e32 v8, 0x3dd53b94, v8
	v_mul_f32_e32 v9, 0x3dd53b94, v9
	v_mul_f32_e32 v10, 0x3dd53b94, v10
	v_cvt_pk_bf16_f32 v154, v1, v4
	v_cvt_pk_bf16_f32 v155, v8, v5
	v_cvt_pk_bf16_f32 v156, v9, v6
	v_cvt_pk_bf16_f32 v157, v10, v7
	s_waitcnt vmcnt(6)
	v_lshlrev_b32_e32 v1, 16, v150
	v_and_b32_e32 v4, 0xffff0000, v150
	v_lshlrev_b32_e32 v8, 16, v151
	v_and_b32_e32 v5, 0xffff0000, v151
	v_lshlrev_b32_e32 v9, 16, v152
	v_and_b32_e32 v6, 0xffff0000, v152
	v_lshlrev_b32_e32 v10, 16, v153
	v_and_b32_e32 v7, 0xffff0000, v153
	v_mul_f32_e32 v4, 0x3dd53b94, v4
	v_mul_f32_e32 v5, 0x3dd53b94, v5
	v_mul_f32_e32 v6, 0x3dd53b94, v6
	v_mul_f32_e32 v7, 0x3dd53b94, v7
	v_mul_f32_e32 v1, 0x3dd53b94, v1
	v_mul_f32_e32 v8, 0x3dd53b94, v8
	v_mul_f32_e32 v9, 0x3dd53b94, v9
	v_mul_f32_e32 v10, 0x3dd53b94, v10
	v_cvt_pk_bf16_f32 v150, v1, v4
	v_cvt_pk_bf16_f32 v151, v8, v5
	v_cvt_pk_bf16_f32 v152, v9, v6
	v_cvt_pk_bf16_f32 v153, v10, v7
	s_waitcnt vmcnt(5)
; __device__ __forceinline__ float bf2f(unsigned h) { return __uint_as_float(h << 16); }
; __device__ __forceinline__ void mla_unit(char* lds, const bf16_t* __restrict__ Qp, const bf16_t* __restrict__ Knp, const bf16_t* __restrict__ Vp, ...
;     ...
;   for (int d0 = 0; d0 < 8; ++d0) { const u32x4 raw = *reinterpret_cast<const u32x4*>(Qw + d0 * 16); u32x4 w;
; #pragma unroll
;     for (int p = 0; p < 4; ++p) w[p] = cvtpk(bf2f(raw[p] & 0xffffu) * C, bf2f(raw[p] >> 16) * C);
;     qr[d0] = *reinterpret_cast<bf16x8*>(&w); }
;   { const int pos = pos0 + wid * QBLK + r32;
; #pragma unroll
;     for (int d0 = 0; d0 < 4; ++d0) {
;       const u32x4 raw = *reinterpret_cast<const u32x4*>(Qw + 128 + d0 * 16);
;       const int i0 = d0 * 8 + hi * 4;
;       const f32x4 cc = *reinterpret_cast<const f32x4*>(cs_tab + pos * 32 + i0) * C, ss = *reinterpret_cast<const f32x4*>(sn_tab + pos * 32 + i0) * C;
;       u32x4 w;
; #pragma unroll
;       for (int p = 0; p < 4; ++p) { const float x1 = bf2f(raw[p] & 0xffffu), x2 = bf2f(raw[p] >> 16); w[p] = cvtpk(x1 * cc[p] - x2 * ss[p], x1 * ss[p] + x2 * cc[p]); }
;       qr[8 + d0] = *reinterpret_cast<bf16x8*>(&w);
;     } }
	v_lshlrev_b32_e32 v8, 16, v147
	v_lshlrev_b32_e32 v9, 16, v148
	v_and_b32_e32 v6, 0xffff0000, v148
	v_lshlrev_b32_e32 v10, 16, v149
	v_and_b32_e32 v7, 0xffff0000, v149
	v_lshlrev_b32_e32 v1, 16, v146
	v_and_b32_e32 v4, 0xffff0000, v146
	v_and_b32_e32 v5, 0xffff0000, v147
	v_mul_f32_e32 v8, 0x3dd53b94, v8
	v_mul_f32_e32 v9, 0x3dd53b94, v9
	v_mul_f32_e32 v6, 0x3dd53b94, v6
	v_mul_f32_e32 v7, 0x3dd53b94, v7
	v_mul_f32_e32 v1, 0x3dd53b94, v1
	v_mul_f32_e32 v4, 0x3dd53b94, v4
	v_mul_f32_e32 v5, 0x3dd53b94, v5
	v_mul_f32_e32 v10, 0x3dd53b94, v10
	v_cvt_pk_bf16_f32 v146, v1, v4
	v_cvt_pk_bf16_f32 v147, v8, v5
	v_cvt_pk_bf16_f32 v148, v9, v6
	v_cvt_pk_bf16_f32 v149, v10, v7
	v_or_b32_e32 v1, s1, v196
	v_add_lshl_u32 v4, v1, s39, 5
	v_ashrrev_i32_e32 v5, 31, v4
	v_lshlrev_b64 v[4:5], 2, v[4:5]
	v_lshl_add_u64 v[10:11], s[34:35], 0, v[4:5]
	v_lshl_add_u64 v[12:13], s[86:87], 0, v[4:5]
	v_lshl_add_u64 v[4:5], v[10:11], 0, v[194:195]
	v_lshl_add_u64 v[18:19], v[12:13], 0, v[194:195]
	s_add_i32 s1, 0, 0x18000
	v_add_u32_e32 v206, s1, v205
	s_waitcnt vmcnt(4)
	v_lshlrev_b32_e32 v1, 16, v158
	v_and_b32_e32 v6, 0xffff0000, v158
	v_lshlrev_b32_e32 v10, 16, v159
	v_and_b32_e32 v7, 0xffff0000, v159
	v_lshlrev_b32_e32 v11, 16, v160
	v_and_b32_e32 v8, 0xffff0000, v160
	v_lshlrev_b32_e32 v14, 16, v161
	v_and_b32_e32 v9, 0xffff0000, v161
	v_mul_f32_e32 v6, 0x3dd53b94, v6
	v_mul_f32_e32 v10, 0x3dd53b94, v10
	v_mul_f32_e32 v7, 0x3dd53b94, v7
	v_mul_f32_e32 v11, 0x3dd53b94, v11
	v_mul_f32_e32 v8, 0x3dd53b94, v8
	v_mul_f32_e32 v14, 0x3dd53b94, v14
	v_mul_f32_e32 v9, 0x3dd53b94, v9
	v_mul_f32_e32 v1, 0x3dd53b94, v1
	v_cvt_pk_bf16_f32 v158, v1, v6
	v_cvt_pk_bf16_f32 v159, v10, v7
	v_cvt_pk_bf16_f32 v160, v11, v8
	v_cvt_pk_bf16_f32 v161, v14, v9
	global_load_dwordx4 v[10:13], v[4:5], off
	global_load_dwordx4 v[14:17], v[18:19], off
	s_waitcnt vmcnt(1)
	v_mov_b32_e32 v22, v10
	s_waitcnt vmcnt(0)
	v_mov_b32_e32 v23, v14
	v_mov_b32_e32 v14, v11
	v_mov_b32_e32 v24, v12
	v_mov_b32_e32 v25, v16
	v_mov_b32_e32 v16, v13
	v_lshlrev_b32_e32 v20, 16, v162
	v_and_b32_e32 v21, 0xffff0000, v162
	v_lshlrev_b32_e32 v6, 16, v163
	v_and_b32_e32 v7, 0xffff0000, v163
	v_lshlrev_b32_e32 v10, 16, v164
	v_and_b32_e32 v11, 0xffff0000, v164
	v_lshlrev_b32_e32 v8, 16, v165
	v_and_b32_e32 v9, 0xffff0000, v165
	v_pk_mul_f32 v[12:13], v[22:23], s[6:7] op_sel_hi:[1,0]
	v_pk_mul_f32 v[14:15], v[14:15], s[6:7] op_sel_hi:[1,0]
	v_pk_mul_f32 v[22:23], v[24:25], s[6:7] op_sel_hi:[1,0]
	v_pk_mul_f32 v[16:17], v[16:17], s[6:7] op_sel_hi:[1,0]
	v_pk_mul_f32 v[24:25], v[12:13], v[20:21]
	v_pk_mul_f32 v[12:13], v[12:13], v[20:21] op_sel:[0,1] op_sel_hi:[1,0]
	v_pk_mul_f32 v[20:21], v[14:15], v[6:7]
	v_pk_mul_f32 v[6:7], v[14:15], v[6:7] op_sel:[0,1] op_sel_hi:[1,0]
	v_pk_mul_f32 v[14:15], v[22:23], v[10:11]
	v_pk_mul_f32 v[10:11], v[22:23], v[10:11] op_sel:[0,1] op_sel_hi:[1,0]
	v_pk_mul_f32 v[22:23], v[16:17], v[8:9]
	v_pk_mul_f32 v[8:9], v[16:17], v[8:9] op_sel:[0,1] op_sel_hi:[1,0]
	v_add_f32_e32 v12, v12, v13
	v_sub_f32_e32 v13, v20, v21
	v_add_f32_e32 v6, v6, v7
	v_sub_f32_e32 v7, v14, v15
	v_add_f32_e32 v10, v10, v11
	v_sub_f32_e32 v11, v22, v23
	v_add_f32_e32 v8, v8, v9
	v_sub_f32_e32 v1, v24, v25
	v_cvt_pk_bf16_f32 v162, v1, v12
	v_cvt_pk_bf16_f32 v163, v13, v6
	v_cvt_pk_bf16_f32 v164, v7, v10
	v_cvt_pk_bf16_f32 v165, v11, v8
	global_load_dwordx4 v[10:13], v[4:5], off offset:32
	global_load_dwordx4 v[14:17], v[18:19], off offset:32
	s_waitcnt vmcnt(2)
	v_lshlrev_b32_e32 v20, 16, v166
	s_waitcnt vmcnt(1)
	v_mov_b32_e32 v22, v10
	s_waitcnt vmcnt(0)
	v_mov_b32_e32 v23, v14
	v_mov_b32_e32 v14, v11
	v_mov_b32_e32 v24, v12
	v_mov_b32_e32 v25, v16
	v_mov_b32_e32 v16, v13
	v_and_b32_e32 v21, 0xffff0000, v166
	v_lshlrev_b32_e32 v6, 16, v167
	v_and_b32_e32 v7, 0xffff0000, v167
	v_lshlrev_b32_e32 v10, 16, v168
	v_and_b32_e32 v11, 0xffff0000, v168
	v_lshlrev_b32_e32 v8, 16, v169
	v_and_b32_e32 v9, 0xffff0000, v169
	v_pk_mul_f32 v[12:13], v[22:23], s[6:7] op_sel_hi:[1,0]
	v_pk_mul_f32 v[14:15], v[14:15], s[6:7] op_sel_hi:[1,0]
	v_pk_mul_f32 v[22:23], v[24:25], s[6:7] op_sel_hi:[1,0]
	v_pk_mul_f32 v[16:17], v[16:17], s[6:7] op_sel_hi:[1,0]
	v_pk_mul_f32 v[24:25], v[12:13], v[20:21]
	v_pk_mul_f32 v[12:13], v[12:13], v[20:21] op_sel:[0,1] op_sel_hi:[1,0]
	v_pk_mul_f32 v[20:21], v[14:15], v[6:7]
	v_pk_mul_f32 v[6:7], v[14:15], v[6:7] op_sel:[0,1] op_sel_hi:[1,0]
	v_pk_mul_f32 v[14:15], v[22:23], v[10:11]
	v_pk_mul_f32 v[10:11], v[22:23], v[10:11] op_sel:[0,1] op_sel_hi:[1,0]
	v_pk_mul_f32 v[22:23], v[16:17], v[8:9]
	v_pk_mul_f32 v[8:9], v[16:17], v[8:9] op_sel:[0,1] op_sel_hi:[1,0]
	v_add_f32_e32 v12, v12, v13
	v_sub_f32_e32 v13, v20, v21
	v_add_f32_e32 v6, v6, v7
	v_sub_f32_e32 v7, v14, v15
	v_add_f32_e32 v10, v10, v11
	v_sub_f32_e32 v11, v22, v23
	v_add_f32_e32 v8, v8, v9
	v_sub_f32_e32 v1, v24, v25
	v_cvt_pk_bf16_f32 v166, v1, v12
	v_cvt_pk_bf16_f32 v167, v13, v6
	v_cvt_pk_bf16_f32 v168, v7, v10
	v_cvt_pk_bf16_f32 v169, v11, v8
	global_load_dwordx4 v[10:13], v[4:5], off offset:64
	global_load_dwordx4 v[14:17], v[18:19], off offset:64
	s_waitcnt vmcnt(2)
	v_lshlrev_b32_e32 v20, 16, v170
	s_waitcnt vmcnt(1)
	v_mov_b32_e32 v22, v10
	s_waitcnt vmcnt(0)
; __device__ __forceinline__ float bf2f(unsigned h) { return __uint_as_float(h << 16); }
; __device__ __forceinline__ void qkt192n(f32x16& p0, f32x16& p1, const char* Ks, const char* Kr, const bf16x8* qr, const f32x16& negm, int r32, int hi) {
; #pragma unroll
;   for (int d0 = 0; d0 < 8; ++d0) { const int cb = d0 * 32 + hi * 16;
;     const bf16x8 b0 = *reinterpret_cast<const bf16x8*>(Ks + KSWZ(r32, cb));
;     const bf16x8 b1 = *reinterpret_cast<const bf16x8*>(Ks + KSWZ(32 + r32, cb));
;     if (d0 == 0) { p0 = __builtin_amdgcn_mfma_f32_32x32x16_bf16(b0, qr[0], negm, 0, 0, 0); p1 = __builtin_amdgcn_mfma_f32_32x32x16_bf16(b1, qr[0], negm, 0, 0, 0); }
;     else { p0 = __builtin_amdgcn_mfma_f32_32x32x16_bf16(b0, qr[d0], p0, 0, 0, 0); p1 = __builtin_amdgcn_mfma_f32_32x32x16_bf16(b1, qr[d0], p1, 0, 0, 0); } }
; __device__ __forceinline__ void mla_unit(char* lds, const bf16_t* __restrict__ Qp, const bf16_t* __restrict__ Knp, const bf16_t* __restrict__ Vp, ...
;     ...
;     for (int d0 = 0; d0 < 4; ++d0) {
;       const u32x4 raw = *reinterpret_cast<const u32x4*>(Qw + 128 + d0 * 16);
;       const int i0 = d0 * 8 + hi * 4;
;       const f32x4 cc = *reinterpret_cast<const f32x4*>(cs_tab + pos * 32 + i0) * C, ss = *reinterpret_cast<const f32x4*>(sn_tab + pos * 32 + i0) * C;
;       u32x4 w;
; #pragma unroll
;       for (int p = 0; p < 4; ++p) { const float x1 = bf2f(raw[p] & 0xffffu), x2 = bf2f(raw[p] >> 16); w[p] = cvtpk(x1 * cc[p] - x2 * ss[p], x1 * ss[p] + x2 * cc[p]); }
;       qr[8 + d0] = *reinterpret_cast<bf16x8*>(&w);
;     } }
;   f32x16 pA0, pA1, pB0, pB1; bf16x8 pa0, pa1, pa2, pa3;
;   constexpr float THRL = THR * 1.4426950408889634f;
;   float mhat = 0.f; f32x16 negm = f32x16{}; asm volatile("" : "+v"(negm));
	v_mov_b32_e32 v23, v14
	v_mov_b32_e32 v14, v11
	v_mov_b32_e32 v24, v12
	v_mov_b32_e32 v25, v16
	v_mov_b32_e32 v16, v13
	v_and_b32_e32 v21, 0xffff0000, v170
	v_lshlrev_b32_e32 v6, 16, v171
	v_and_b32_e32 v7, 0xffff0000, v171
	v_lshlrev_b32_e32 v10, 16, v172
	v_and_b32_e32 v11, 0xffff0000, v172
	v_lshlrev_b32_e32 v8, 16, v173
	v_and_b32_e32 v9, 0xffff0000, v173
	v_pk_mul_f32 v[12:13], v[22:23], s[6:7] op_sel_hi:[1,0]
	v_pk_mul_f32 v[14:15], v[14:15], s[6:7] op_sel_hi:[1,0]
	v_pk_mul_f32 v[22:23], v[24:25], s[6:7] op_sel_hi:[1,0]
	v_pk_mul_f32 v[16:17], v[16:17], s[6:7] op_sel_hi:[1,0]
	v_pk_mul_f32 v[24:25], v[12:13], v[20:21]
	v_pk_mul_f32 v[12:13], v[12:13], v[20:21] op_sel:[0,1] op_sel_hi:[1,0]
	v_pk_mul_f32 v[20:21], v[14:15], v[6:7]
	v_pk_mul_f32 v[6:7], v[14:15], v[6:7] op_sel:[0,1] op_sel_hi:[1,0]
	v_pk_mul_f32 v[14:15], v[22:23], v[10:11]
	v_pk_mul_f32 v[10:11], v[22:23], v[10:11] op_sel:[0,1] op_sel_hi:[1,0]
	v_pk_mul_f32 v[22:23], v[16:17], v[8:9]
	v_pk_mul_f32 v[8:9], v[16:17], v[8:9] op_sel:[0,1] op_sel_hi:[1,0]
	v_sub_f32_e32 v1, v24, v25
	v_add_f32_e32 v12, v12, v13
	v_sub_f32_e32 v13, v20, v21
	v_add_f32_e32 v6, v6, v7
	v_sub_f32_e32 v7, v14, v15
	v_add_f32_e32 v10, v10, v11
	v_sub_f32_e32 v11, v22, v23
	v_add_f32_e32 v8, v8, v9
	v_cvt_pk_bf16_f32 v170, v1, v12
	v_cvt_pk_bf16_f32 v171, v13, v6
	v_cvt_pk_bf16_f32 v172, v7, v10
	v_cvt_pk_bf16_f32 v173, v11, v8
	global_load_dwordx4 v[36:39], v[4:5], off offset:96
	global_load_dwordx4 v[40:43], v[18:19], off offset:96
	v_mov_b32_e32 v14, v0
	v_mov_b32_e32 v15, v0
	v_mov_b32_e32 v1, v0
	v_mov_b32_e32 v2, v0
	v_mov_b32_e32 v3, v0
	v_mov_b32_e32 v4, v0
	v_mov_b32_e32 v5, v0
	v_mov_b32_e32 v6, v0
	v_mov_b32_e32 v7, v0
	v_mov_b32_e32 v8, v0
	v_mov_b32_e32 v9, v0
	v_mov_b32_e32 v10, v0
	v_mov_b32_e32 v11, v0
	v_mov_b32_e32 v12, v0
	v_mov_b32_e32 v13, v0
	v_mov_b64_e32 v[30:31], v[14:15]
	v_mov_b64_e32 v[28:29], v[12:13]
	v_mov_b64_e32 v[26:27], v[10:11]
	v_mov_b64_e32 v[24:25], v[8:9]
	v_mov_b64_e32 v[22:23], v[6:7]
	v_mov_b64_e32 v[20:21], v[4:5]
	v_mov_b64_e32 v[18:19], v[2:3]
	v_mov_b64_e32 v[16:17], v[0:1]
	s_waitcnt vmcnt(2)
	v_lshlrev_b32_e32 v44, 16, v174
	s_waitcnt vmcnt(1)
	v_mov_b32_e32 v46, v36
	s_waitcnt vmcnt(0)
	v_mov_b32_e32 v47, v40
	v_mov_b32_e32 v40, v37
	v_mov_b32_e32 v52, v38
	v_mov_b32_e32 v53, v42
	v_mov_b32_e32 v42, v39
	v_and_b32_e32 v45, 0xffff0000, v174
	v_lshlrev_b32_e32 v32, 16, v175
	v_and_b32_e32 v33, 0xffff0000, v175
	v_lshlrev_b32_e32 v36, 16, v176
	v_and_b32_e32 v37, 0xffff0000, v176
	v_lshlrev_b32_e32 v34, 16, v177
	v_and_b32_e32 v35, 0xffff0000, v177
	v_pk_mul_f32 v[38:39], v[46:47], s[6:7] op_sel_hi:[1,0]
	v_pk_mul_f32 v[40:41], v[40:41], s[6:7] op_sel_hi:[1,0]
	v_pk_mul_f32 v[46:47], v[52:53], s[6:7] op_sel_hi:[1,0]
	v_pk_mul_f32 v[42:43], v[42:43], s[6:7] op_sel_hi:[1,0]
	v_pk_mul_f32 v[52:53], v[38:39], v[44:45]
	v_pk_mul_f32 v[38:39], v[38:39], v[44:45] op_sel:[0,1] op_sel_hi:[1,0]
	v_pk_mul_f32 v[44:45], v[40:41], v[32:33]
	v_pk_mul_f32 v[32:33], v[40:41], v[32:33] op_sel:[0,1] op_sel_hi:[1,0]
	v_pk_mul_f32 v[40:41], v[46:47], v[36:37]
	v_pk_mul_f32 v[36:37], v[46:47], v[36:37] op_sel:[0,1] op_sel_hi:[1,0]
	v_pk_mul_f32 v[46:47], v[42:43], v[34:35]
	v_pk_mul_f32 v[34:35], v[42:43], v[34:35] op_sel:[0,1] op_sel_hi:[1,0]
	v_sub_f32_e32 v42, v52, v53
	v_add_f32_e32 v38, v38, v39
	v_sub_f32_e32 v39, v44, v45
	v_add_f32_e32 v32, v32, v33
	v_sub_f32_e32 v33, v40, v41
	v_add_f32_e32 v36, v36, v37
	v_sub_f32_e32 v37, v46, v47
	v_add_f32_e32 v34, v34, v35
	v_cvt_pk_bf16_f32 v174, v42, v38
	v_cvt_pk_bf16_f32 v175, v39, v32
	v_cvt_pk_bf16_f32 v176, v33, v36
	v_cvt_pk_bf16_f32 v177, v37, v34
	s_waitcnt vmcnt(10) lgkmcnt(0)
	s_barrier
	ds_read_b128 v[52:55], v56 offset:49152
	ds_read_b128 v[56:59], v56 offset:57344
	s_waitcnt lgkmcnt(1)
	v_mfma_f32_32x32x16_bf16 v[32:47], v[52:55], v[130:133], v[16:31]
	v_or_b32_e32 v52, 32, v194
	v_xad_u32 v53, v52, v51, v66
	s_waitcnt lgkmcnt(0)
	v_mfma_f32_32x32x16_bf16 v[16:31], v[56:59], v[130:133], v[16:31]
	ds_read_b128 v[54:57], v53 offset:49152
	ds_read_b128 v[58:61], v53 offset:57344
	v_or_b32_e32 v53, 64, v194
	v_xad_u32 v62, v53, v51, v66
	s_waitcnt lgkmcnt(1)
	v_mfma_f32_32x32x16_bf16 v[32:47], v[54:57], v[134:137], v[32:47]
	s_waitcnt lgkmcnt(0)
	v_mfma_f32_32x32x16_bf16 v[16:31], v[58:61], v[134:137], v[16:31]
	ds_read_b128 v[54:57], v62 offset:49152
	ds_read_b128 v[58:61], v62 offset:57344
	s_waitcnt lgkmcnt(1)
	v_mfma_f32_32x32x16_bf16 v[32:47], v[54:57], v[138:141], v[32:47]
	v_or_b32_e32 v54, 0x60, v194
	v_xad_u32 v55, v54, v51, v66
	s_waitcnt lgkmcnt(0)
	v_mfma_f32_32x32x16_bf16 v[16:31], v[58:61], v[138:141], v[16:31]
	ds_read_b128 v[56:59], v55 offset:49152
	ds_read_b128 v[60:63], v55 offset:57344
	v_or_b32_e32 v55, 0x80, v194
	v_xad_u32 v64, v55, v51, v66
	s_waitcnt lgkmcnt(1)
	v_mfma_f32_32x32x16_bf16 v[32:47], v[56:59], v[142:145], v[32:47]
	s_waitcnt lgkmcnt(0)
	v_mfma_f32_32x32x16_bf16 v[16:31], v[60:63], v[142:145], v[16:31]
	ds_read_b128 v[56:59], v64 offset:49152
	ds_read_b128 v[60:63], v64 offset:57344
	s_waitcnt lgkmcnt(1)
	v_mfma_f32_32x32x16_bf16 v[32:47], v[56:59], v[154:157], v[32:47]
	v_or_b32_e32 v56, 0xa0, v194
	v_xad_u32 v57, v56, v51, v66
	s_waitcnt lgkmcnt(0)
	v_mfma_f32_32x32x16_bf16 v[16:31], v[60:63], v[154:157], v[16:31]
	ds_read_b128 v[58:61], v57 offset:49152
	ds_read_b128 v[62:65], v57 offset:57344
	v_or_b32_e32 v57, 0xc0, v194
	v_xad_u32 v67, v57, v51, v66
	s_waitcnt lgkmcnt(1)
	v_mfma_f32_32x32x16_bf16 v[32:47], v[58:61], v[150:153], v[32:47]
	s_waitcnt lgkmcnt(0)
	v_mfma_f32_32x32x16_bf16 v[16:31], v[62:65], v[150:153], v[16:31]
	ds_read_b128 v[58:61], v67 offset:49152
	ds_read_b128 v[62:65], v67 offset:57344
	s_waitcnt lgkmcnt(1)
; __device__ __forceinline__ void qkt192n(f32x16& p0, f32x16& p1, const char* Ks, const char* Kr, const bf16x8* qr, const f32x16& negm, int r32, int hi) {
; #pragma unroll
;   for (int d0 = 0; d0 < 8; ++d0) { const int cb = d0 * 32 + hi * 16;
;     const bf16x8 b0 = *reinterpret_cast<const bf16x8*>(Ks + KSWZ(r32, cb));
;     const bf16x8 b1 = *reinterpret_cast<const bf16x8*>(Ks + KSWZ(32 + r32, cb));
;     if (d0 == 0) { p0 = __builtin_amdgcn_mfma_f32_32x32x16_bf16(b0, qr[0], negm, 0, 0, 0); p1 = __builtin_amdgcn_mfma_f32_32x32x16_bf16(b1, qr[0], negm, 0, 0, 0); }
;     else { p0 = __builtin_amdgcn_mfma_f32_32x32x16_bf16(b0, qr[d0], p0, 0, 0, 0); p1 = __builtin_amdgcn_mfma_f32_32x32x16_bf16(b1, qr[d0], p1, 0, 0, 0); } }
; #pragma unroll
;   for (int d0 = 0; d0 < 4; ++d0) { const int cb = d0 * 32 + hi * 16;
;     const bf16x8 b0 = *reinterpret_cast<const bf16x8*>(Kr + RSWZ(r32, cb));
;     const bf16x8 b1 = *reinterpret_cast<const bf16x8*>(Kr + RSWZ(32 + r32, cb));
;     p0 = __builtin_amdgcn_mfma_f32_32x32x16_bf16(b0, qr[8 + d0], p0, 0, 0, 0);
;     p1 = __builtin_amdgcn_mfma_f32_32x32x16_bf16(b1, qr[8 + d0], p1, 0, 0, 0); }
	v_mfma_f32_32x32x16_bf16 v[32:47], v[58:61], v[146:149], v[32:47]
	v_or_b32_e32 v58, 0xe0, v194
	v_xad_u32 v59, v58, v51, v66
	s_waitcnt lgkmcnt(0)
	v_mfma_f32_32x32x16_bf16 v[16:31], v[62:65], v[146:149], v[16:31]
	ds_read_b128 v[60:63], v59 offset:49152
	ds_read_b128 v[64:67], v59 offset:57344
	v_lshlrev_b32_e32 v59, 3, v50
	v_and_b32_e32 v68, 0x70, v59
	v_xad_u32 v69, v194, v68, v206
	v_and_b32_e32 v50, 63, v50
	v_cmp_gt_u32_e64 s[40:41], 32, v50
	s_waitcnt lgkmcnt(1)
	v_mfma_f32_32x32x16_bf16 v[32:47], v[60:63], v[158:161], v[32:47]
	s_waitcnt lgkmcnt(0)
	v_mfma_f32_32x32x16_bf16 v[16:31], v[64:67], v[158:161], v[16:31]
	ds_read_b128 v[60:63], v69
	ds_read_b128 v[64:67], v69 offset:4096
	v_xad_u32 v69, v52, v68, v206
	s_waitcnt lgkmcnt(1)
	v_mfma_f32_32x32x16_bf16 v[32:47], v[60:63], v[162:165], v[32:47]
	s_waitcnt lgkmcnt(0)
	v_mfma_f32_32x32x16_bf16 v[16:31], v[64:67], v[162:165], v[16:31]
	ds_read_b128 v[60:63], v69
	ds_read_b128 v[64:67], v69 offset:4096
	v_xad_u32 v69, v53, v68, v206
	v_xad_u32 v68, v54, v68, v206
	s_waitcnt lgkmcnt(1)
	v_mfma_f32_32x32x16_bf16 v[32:47], v[60:63], v[166:169], v[32:47]
	s_waitcnt lgkmcnt(0)
	v_mfma_f32_32x32x16_bf16 v[16:31], v[64:67], v[166:169], v[16:31]
	ds_read_b128 v[60:63], v69
	ds_read_b128 v[64:67], v69 offset:4096
	s_waitcnt lgkmcnt(1)
	v_mfma_f32_32x32x16_bf16 v[32:47], v[60:63], v[170:173], v[32:47]
	s_waitcnt lgkmcnt(0)
	v_mfma_f32_32x32x16_bf16 v[16:31], v[64:67], v[170:173], v[16:31]
	ds_read_b128 v[60:63], v68
	ds_read_b128 v[64:67], v68 offset:4096
	s_waitcnt lgkmcnt(1)
	v_mfma_f32_32x32x16_bf16 v[32:47], v[60:63], v[174:177], v[32:47]
	s_waitcnt lgkmcnt(0)
; #define MX3(a, b, c) __builtin_fmaxf(__builtin_fmaxf((a), (b)), (c))
; #define MX3(a, b, c) __builtin_fmaxf(__builtin_fmaxf((a), (b)), (c))
; __device__ __forceinline__ float rowmax32(const f32x16& p0, const f32x16& p1) {
;   float a = MX3(p0[0], p0[1], p1[0]), b = MX3(p0[2], p0[3], p1[1]); a = MX3(a, p1[2], p1[3]);
; #pragma unroll
;   for (int r = 4; r < 16; r += 4) { a = MX3(a, p0[r], p0[r + 1]); b = MX3(b, p0[r + 2], p0[r + 3]); a = MX3(a, p1[r], p1[r + 1]); b = MX3(b, p1[r + 2], p1[r + 3]); }
;   float m = __builtin_fmaxf(a, b);
;   auto rr = __builtin_amdgcn_permlane32_swap(__float_as_uint(m), __float_as_uint(m), false, false);
;   return __builtin_fmaxf(__uint_as_float(rr[0]), __uint_as_float(rr[1]));
; }
; __device__ __forceinline__ void mla_unit(char* lds, const bf16_t* __restrict__ Qp, const bf16_t* __restrict__ Knp, const bf16_t* __restrict__ Vp, ...
;     ...
;   bool resc = false; float sum0 = 0.f;
	v_mfma_f32_32x32x16_bf16 v[16:31], v[64:67], v[174:177], v[16:31]
	s_nop 9
	v_max_f32_e32 v60, v33, v33
	v_max_f32_e32 v61, v32, v32
	v_max_f32_e32 v60, v61, v60
	v_max3_f32 v62, v34, v35, v17
	v_max3_f32 v60, v60, v16, v18
	v_max3_f32 v61, v62, v38, v39
	v_max3_f32 v60, v60, v19, v36
	v_max3_f32 v61, v61, v22, v23
	v_max3_f32 v60, v60, v37, v20
	v_max3_f32 v61, v61, v42, v43
	v_max3_f32 v60, v60, v21, v40
	v_max3_f32 v61, v61, v26, v27
	v_max3_f32 v60, v60, v41, v24
	v_max3_f32 v61, v61, v46, v47
	v_max3_f32 v60, v60, v25, v44
	v_max3_f32 v61, v61, v30, v31
	v_max3_f32 v60, v60, v45, v28
	v_max3_f32 v60, v60, v29, v61
	v_mov_b32_e32 v61, v60
	s_nop 1
	v_permlane32_swap_b32_e32 v60, v61
	v_max_f32_e32 v61, v61, v61
	v_max_f32_e32 v60, v60, v60
	v_max_f32_e32 v61, v60, v61
	v_exp_f32_e64 v60, -v61
	v_add_f32_e32 v203, 0, v61
	v_xor_b32_e32 v66, 0x80000000, v203
	v_mov_b32_e32 v67, v66
	v_mov_b32_e32 v68, v66
	v_mov_b32_e32 v69, v66
	v_mov_b32_e32 v70, v66
	v_mov_b32_e32 v71, v66
	v_mov_b32_e32 v72, v66
	v_mov_b32_e32 v73, v66
	v_mov_b32_e32 v74, v66
	v_mov_b32_e32 v75, v66
	v_mov_b32_e32 v76, v66
	v_mov_b32_e32 v77, v66
	v_mov_b32_e32 v78, v66
	v_mov_b32_e32 v79, v66
	v_mov_b32_e32 v80, v66
	v_mov_b32_e32 v81, v66
	s_and_saveexec_b64 s[6:7], s[40:41]
	ds_write_b32 v200, v60 offset:128
	s_or_b64 exec, exec, s[6:7]
	v_sub_f32_e32 v32, v32, v61
	v_sub_f32_e32 v33, v33, v61
	v_sub_f32_e32 v82, v16, v61
	v_exp_f32_e32 v16, v32
	v_sub_f32_e32 v34, v34, v61
	v_sub_f32_e32 v83, v17, v61
	v_exp_f32_e32 v17, v33
	v_sub_f32_e32 v35, v35, v61
	v_sub_f32_e32 v84, v18, v61
	v_exp_f32_e32 v18, v34
	v_sub_f32_e32 v36, v36, v61
	v_sub_f32_e32 v85, v19, v61
	v_exp_f32_e32 v19, v35
	v_sub_f32_e32 v37, v37, v61
	v_sub_f32_e32 v86, v20, v61
	v_exp_f32_e32 v20, v36
	v_add_f32_e32 v32, 0, v16
	v_sub_f32_e32 v38, v38, v61
	v_sub_f32_e32 v87, v21, v61
	v_exp_f32_e32 v21, v37
	v_add_f32_e32 v32, v17, v32
	v_sub_f32_e32 v39, v39, v61
	v_sub_f32_e32 v88, v22, v61
	v_exp_f32_e32 v22, v38
	v_add_f32_e32 v32, v18, v32
	v_sub_f32_e32 v40, v40, v61
	v_sub_f32_e32 v89, v23, v61
	v_exp_f32_e32 v23, v39
	v_add_f32_e32 v32, v19, v32
	v_sub_f32_e32 v41, v41, v61
	v_sub_f32_e32 v90, v24, v61
	v_exp_f32_e32 v24, v40
	v_add_f32_e32 v32, v20, v32
	v_sub_f32_e32 v42, v42, v61
	v_sub_f32_e32 v91, v25, v61
	v_exp_f32_e32 v25, v41
	v_add_f32_e32 v32, v21, v32
	v_sub_f32_e32 v43, v43, v61
	v_sub_f32_e32 v92, v26, v61
	v_exp_f32_e32 v26, v42
	v_add_f32_e32 v32, v22, v32
	v_sub_f32_e32 v44, v44, v61
	v_sub_f32_e32 v93, v27, v61
	v_exp_f32_e32 v27, v43
	v_add_f32_e32 v32, v23, v32
	v_sub_f32_e32 v45, v45, v61
	v_sub_f32_e32 v94, v28, v61
	v_exp_f32_e32 v28, v44
	v_add_f32_e32 v32, v24, v32
	s_lshr_b32 s69, s74, 5
	v_sub_f32_e32 v46, v46, v61
	v_sub_f32_e32 v95, v29, v61
	v_exp_f32_e32 v29, v45
	v_add_f32_e32 v32, v25, v32
	v_sub_f32_e32 v47, v47, v61
	v_sub_f32_e32 v96, v30, v61
	s_and_b32 s0, s69, 15
	v_exp_f32_e32 v30, v46
	v_add_f32_e32 v32, v26, v32
	s_movk_i32 s1, 0x70
	v_sub_f32_e32 v97, v31, v61
	s_lshl_b32 s0, s0, 23
	v_exp_f32_e32 v31, v47
	v_add_f32_e32 v32, v27, v32
	v_bitop3_b32 v221, v194, v59, s1 bitop3:0x78
	v_bitop3_b32 v209, v52, v59, s1 bitop3:0x78
	v_bitop3_b32 v208, v53, v59, s1 bitop3:0x78
	v_bitop3_b32 v207, v54, v59, s1 bitop3:0x78
	v_readlane_b32 s1, v254, 9
	v_lshlrev_b32_e32 v62, 4, v50
	v_add_f32_e32 v32, v28, v32
	s_add_u32 s36, s1, s36
	v_readlane_b32 s1, v254, 10
	v_lshlrev_b32_e32 v195, 2, v49
	v_lshlrev_b32_e32 v49, 3, v50
	v_and_b32_e32 v62, 0xc0, v62
	v_lshlrev_b32_e32 v50, 1, v50
	v_add_f32_e32 v32, v29, v32
	s_addc_u32 s37, s1, s37
	v_and_or_b32 v62, v49, 24, v62
	v_and_b32_e32 v50, 32, v50
	v_and_b32_e32 v49, 0x100, v49
	v_add_f32_e32 v32, v30, v32
	s_add_u32 s0, s0, s30
	v_or3_b32 v201, v62, v50, v49
	v_mul_f32_e32 v234, 0, v60
	v_add_f32_e32 v186, v31, v32
	v_cvt_pk_bf16_f32 v182, v16, v17
	v_cvt_pk_bf16_f32 v183, v18, v19
	v_cvt_pk_bf16_f32 v184, v20, v21
	v_cvt_pk_bf16_f32 v185, v22, v23
	v_cvt_pk_bf16_f32 v178, v24, v25
	v_cvt_pk_bf16_f32 v179, v26, v27
	v_cvt_pk_bf16_f32 v180, v28, v29
	v_cvt_pk_bf16_f32 v181, v30, v31
	v_bitop3_b32 v229, v194, v48, s53 bitop3:0x78
	v_bitop3_b32 v230, v194, v204, v51 bitop3:0xde
	v_bitop3_b32 v228, v52, v48, s53 bitop3:0x78
	v_bitop3_b32 v231, v52, v204, v51 bitop3:0xde
	v_bitop3_b32 v227, v53, v48, s53 bitop3:0x78
	v_bitop3_b32 v226, v54, v48, s53 bitop3:0x78
	v_bitop3_b32 v225, v55, v48, s53 bitop3:0x78
	v_bitop3_b32 v224, v56, v48, s53 bitop3:0x78
	v_bitop3_b32 v223, v57, v48, s53 bitop3:0x78
	v_bitop3_b32 v222, v58, v48, s53 bitop3:0x78
	s_addc_u32 s1, 0, s31
	v_readlane_b32 s12, v254, 35
	v_mov_b64_e32 v[64:65], v[14:15]
	v_mov_b64_e32 v[48:49], v[14:15]
	v_mov_b64_e32 v[32:33], v[14:15]
	v_readlane_b32 s13, v254, 36
	s_add_u32 s30, s12, s0
	v_mov_b64_e32 v[62:63], v[12:13]
	v_mov_b64_e32 v[60:61], v[10:11]
	v_mov_b64_e32 v[58:59], v[8:9]
	v_mov_b64_e32 v[56:57], v[6:7]
	v_mov_b64_e32 v[54:55], v[4:5]
	v_mov_b64_e32 v[52:53], v[2:3]
	v_mov_b64_e32 v[50:51], v[0:1]
	v_mov_b64_e32 v[46:47], v[12:13]
	v_mov_b64_e32 v[44:45], v[10:11]
	v_mov_b64_e32 v[42:43], v[8:9]
	v_mov_b64_e32 v[40:41], v[6:7]
	v_mov_b64_e32 v[38:39], v[4:5]
	v_mov_b64_e32 v[36:37], v[2:3]
	v_mov_b64_e32 v[34:35], v[0:1]
	v_mov_b64_e32 v[30:31], v[12:13]
	v_mov_b64_e32 v[28:29], v[10:11]
	v_mov_b64_e32 v[26:27], v[8:9]
	v_mov_b64_e32 v[24:25], v[6:7]
	v_mov_b64_e32 v[22:23], v[4:5]
	v_mov_b64_e32 v[20:21], v[2:3]
	v_mov_b64_e32 v[18:19], v[0:1]
	v_mov_b64_e32 v[16:17], v[14:15]
	s_mov_b32 s70, 1
	v_add_u32_e32 v202, 0, v201
	v_permlane32_swap_b32_e32 v182, v184
	v_permlane32_swap_b32_e32 v183, v185
	v_permlane32_swap_b32_e32 v178, v180
	v_permlane32_swap_b32_e32 v179, v181
	s_mov_b32 s77, 2
	v_add_u32_e32 v232, v229, v204
	v_add_u32_e32 v233, v228, v204
	s_addc_u32 s31, s13, s1
	s_mov_b32 s78, 0
	v_mov_b64_e32 v[14:15], v[12:13]
	v_mov_b64_e32 v[12:13], v[10:11]
	v_mov_b64_e32 v[10:11], v[8:9]
	v_mov_b64_e32 v[8:9], v[6:7]
	v_mov_b64_e32 v[6:7], v[4:5]
	v_mov_b64_e32 v[4:5], v[2:3]
	v_mov_b64_e32 v[2:3], v[0:1]
	s_mov_b32 s0, 0
	v_readlane_b32 s14, v254, 37
	v_readlane_b32 s15, v254, 38

; __device__ __forceinline__ float bf2f(unsigned h) { return __uint_as_float(h << 16); }
; __device__ __forceinline__ void na_unit3(char* lds, const bf16_t* __restrict__ Qp, const bf16_t* __restrict__ Knp, const bf16_t* __restrict__ Vp, ...
;     ...
;   const unsigned lds0 = (unsigned)(uintptr_t)lds;
;   const int pk = (wid & 3) + 8 * (wid >> 2);
;   const int krow_n = 4 * pk + (lane >> 4);
;   const unsigned kn_off = (unsigned)(krow_n * LDK + (((lane & 15) ^ (krow_n & 15)) << 3)) * 2u;
;   const int vst_ = 2 * wid + (lane >> 5), vkk = (vst_ >> 2) * 8 + ((lane >> 2) & 7), vkey = (vkk & ~0xC) | ((vkk & 4) << 1) | ((vkk & 8) >> 1), vcol = (vst_ & 3) * 32 + (lane & 3) * 8;
;   const unsigned v_off = (unsigned)(vkey * LDK + vcol) * 2u;
;   const unsigned kn_dst = lds0 + N_KN + pk * 1024, v_dst = lds0 + N_V + wid * 1024;
;     ...
;   DMA_T(0, 0); DMA_T(1, 1); DMA_T(2, 2);
;   float l_reg = 0.f; f32x16 o[4] = {}; bf16x8 qr[8];
;   const bf16_t* Qw = Qp + (long)(wid * QBLK + r32) * LDQ + hi * 8;
; #pragma unroll
;   for (int d0 = 0; d0 < 8; ++d0) { const u32x4 raw = *reinterpret_cast<const u32x4*>(Qw + d0 * 16); u32x4 w;
; #pragma unroll
;     for (int p = 0; p < 4; ++p) w[p] = cvtpk(bf2f(raw[p] & 0xffffu) * C, bf2f(raw[p] >> 16) * C);
;     qr[d0] = *reinterpret_cast<bf16x8*>(&w); }
.LBB0_276:
	s_lshl_b32 s1, s76, 2
	s_ashr_i32 s30, s76, 9
	s_and_b32 s1, s1, 0x7c
	v_sub_u32_e64 v1, s1, 4 clamp
	s_ashr_i32 s31, s30, 31
	v_readfirstlane_b32 s85, v1
	s_lshl_b64 s[8:9], s[30:31], 13
	s_lshl_b32 s5, s1, 6
	s_or_b32 s34, s8, s5
	s_lshl_b32 s5, s85, 6
	s_or_b32 s8, s8, s5
	s_lshl_b32 s5, s76, 17
	s_lshr_b32 s0, s76, 5
	s_bfe_u32 s77, s76, 0x40005
	s_and_b32 s5, s5, 0x3800000
	s_add_u32 s5, s90, s5
	s_addc_u32 s6, s91, 0
	s_lshl_b32 s7, s76, 3
	s_and_b32 s7, s7, 0x100
	s_mov_b32 s35, s9
	s_add_u32 s81, s5, s7
	s_addc_u32 s84, s6, 0
	s_lshl_b64 s[6:7], s[34:35], 9
	s_add_u32 s6, s81, s6
	s_addc_u32 s7, s84, s7
	s_lshl_b64 s[8:9], s[8:9], 9
	s_add_u32 s5, s81, s8
	s_addc_u32 s14, s84, s9
	s_add_u32 s64, s5, 0x4000000
	s_addc_u32 s65, s14, 0
	v_mov_b32_e32 v2, v252
	s_add_u32 s78, s5, 0x8000000
	s_addc_u32 s79, s14, 0
	v_readfirstlane_b32 s10, v2
	s_ashr_i32 s15, s10, 6
	s_ashr_i32 s9, s10, 5
	s_and_b32 s8, s15, 3
	s_and_b32 s9, s9, -8
	s_or_b32 s8, s8, s9
	s_lshl_b32 s9, s8, 2
	v_bfe_u32 v1, v2, 4, 2
	v_or_b32_e32 v3, s9, v1
	v_bitop3_b32 v1, s9, v2, v1 bitop3:0x36
	s_ashr_i32 s12, s10, 4
	v_lshlrev_b32_e32 v3, 9, v3
	v_lshlrev_b32_e32 v1, 4, v1
	s_and_b32 s13, s12, 0x7ffff0
	s_lshr_b32 s12, s12, 1
	v_and_or_b32 v223, v1, s53, v3
	s_lshl_b32 s9, s15, 1
	v_lshrrev_b32_e32 v1, 2, v2
	v_lshrrev_b32_e32 v3, 1, v2
	s_and_b32 s12, s12, 4
	s_lshl_b32 s8, s8, 10
	v_bfe_u32 v222, v2, 5, 1
	v_and_or_b32 v1, v1, 3, s13
	v_and_b32_e32 v3, 8, v3
	s_cmp_lg_u32 0, -1
	v_or3_b32 v1, v1, v3, s12
	v_and_or_b32 v3, s9, 2, v222
	s_cselect_b32 s9, 0, 0
	s_add_i32 s16, s9, s8
	s_lshl_b32 s89, s15, 10
	v_lshlrev_b32_e32 v18, 4, v2
	s_add_i32 s88, s16, 0x10000
	s_add_i32 s89, s89, s9
	s_mov_b32 m0, s88
	s_nop 0
	global_load_lds_dwordx4 v223, s[64:65]
	v_and_b32_e32 v4, 48, v18
	s_add_u32 s8, s5, 0x4002000
	v_lshl_or_b32 v3, v3, 6, v4
	s_addc_u32 s9, s14, 0
	s_add_i32 s12, s88, 0x1000
	s_mov_b32 m0, s12
	s_nop 0
	global_load_lds_dwordx4 v223, s[8:9]
	v_lshl_or_b32 v224, v1, 9, v3
	s_mov_b32 m0, s89
	s_nop 0
	global_load_lds_dwordx4 v224, s[78:79]
	s_add_u32 s8, s5, 0x8004000
	s_addc_u32 s9, s14, 0
	s_add_i32 s12, s89, 0x2000
	s_mov_b32 m0, s12
	s_nop 0
	global_load_lds_dwordx4 v224, s[8:9]
	s_add_u32 s8, s5, 0x4008000
	s_addc_u32 s9, s14, 0
	s_add_u32 s12, s5, 0x8008000
	s_addc_u32 s13, s14, 0
	s_add_i32 s17, s16, 0x14000
	s_add_i32 s18, s89, 0x4000
	s_mov_b32 m0, s17
	s_nop 0
	global_load_lds_dwordx4 v223, s[8:9]
	s_add_u32 s8, s5, 0x400a000
	s_addc_u32 s9, s14, 0
	s_add_i32 s17, s16, 0x15000
	s_mov_b32 m0, s17
	s_nop 0
	global_load_lds_dwordx4 v223, s[8:9]
	s_mov_b32 m0, s18
	s_nop 0
	global_load_lds_dwordx4 v224, s[12:13]
	s_add_u32 s8, s5, 0x800c000
	s_addc_u32 s9, s14, 0
	s_add_i32 s12, s89, 0x6000
	s_mov_b32 m0, s12
	s_nop 0
	global_load_lds_dwordx4 v224, s[8:9]
	s_add_u32 s8, s5, 0x4010000
	s_addc_u32 s9, s14, 0
	s_add_u32 s12, s5, 0x8010000
	s_addc_u32 s13, s14, 0
	s_add_i32 s17, s16, 0x18000
	s_add_i32 s18, s89, 0x8000
	s_mov_b32 m0, s17
	s_nop 0
	global_load_lds_dwordx4 v223, s[8:9]
	s_add_u32 s8, s5, 0x4012000
	s_addc_u32 s9, s14, 0
	s_add_i32 s16, s16, 0x19000
	s_mov_b32 m0, s16
	s_nop 0
	global_load_lds_dwordx4 v223, s[8:9]
	s_mov_b32 m0, s18
	s_nop 0
	global_load_lds_dwordx4 v224, s[12:13]
	s_add_u32 s8, s5, 0x8014000
	v_and_b32_e32 v221, 31, v2
	s_addc_u32 s9, s14, 0
	s_lshl_b32 s80, s15, 5
	v_or_b32_e32 v4, s80, v221
	v_ashrrev_i32_e32 v5, 31, v4
	v_lshlrev_b64 v[4:5], 9, v[4:5]
	v_lshl_add_u64 v[4:5], s[6:7], 0, v[4:5]
	v_lshlrev_b32_e32 v204, 4, v222
	v_mov_b32_e32 v205, v0
	s_add_i32 s5, s89, 0xa000
	s_mov_b32 m0, s5
	s_nop 0
	global_load_lds_dwordx4 v224, s[8:9]
	v_lshl_add_u64 v[8:9], v[4:5], 0, v[204:205]
	global_load_dwordx4 v[160:163], v[8:9], off nt
	global_load_dwordx4 v[164:167], v[8:9], off offset:32 nt
	global_load_dwordx4 v[168:171], v[8:9], off offset:64 nt
	global_load_dwordx4 v[172:175], v[8:9], off offset:96 nt
	global_load_dwordx4 v[176:179], v[8:9], off offset:128 nt
	global_load_dwordx4 v[180:183], v[8:9], off offset:160 nt
	global_load_dwordx4 v[184:187], v[8:9], off offset:192 nt
	global_load_dwordx4 v[188:191], v[8:9], off offset:224 nt
	s_movk_i32 s5, 0x1d1
	v_cmp_gt_i32_e32 vcc, s5, v2
	s_waitcnt vmcnt(7)
	v_lshlrev_b32_e32 v1, 16, v160
	v_and_b32_e32 v3, 0xffff0000, v160
	v_mul_f32_e32 v1, 0x3e0293ee, v1
	v_mul_f32_e32 v3, 0x3e0293ee, v3
	v_cvt_pk_bf16_f32 v160, v1, v3
	v_and_b32_e32 v1, 0xffff0000, v162
	v_lshlrev_b32_e32 v4, 16, v161
	v_and_b32_e32 v5, 0xffff0000, v161
	v_lshlrev_b32_e32 v10, 16, v162
	v_mul_f32_e32 v1, 0x3e0293ee, v1
	v_mul_f32_e32 v4, 0x3e0293ee, v4
	v_mul_f32_e32 v5, 0x3e0293ee, v5
	v_mul_f32_e32 v10, 0x3e0293ee, v10
	v_cvt_pk_bf16_f32 v161, v4, v5
	v_cvt_pk_bf16_f32 v162, v10, v1
	v_lshlrev_b32_e32 v1, 16, v163
	v_and_b32_e32 v3, 0xffff0000, v163
	v_mul_f32_e32 v1, 0x3e0293ee, v1
	v_mul_f32_e32 v3, 0x3e0293ee, v3
	v_cvt_pk_bf16_f32 v163, v1, v3
	s_waitcnt vmcnt(6)
	v_lshlrev_b32_e32 v1, 16, v164
	v_and_b32_e32 v3, 0xffff0000, v164
	v_lshlrev_b32_e32 v4, 16, v165
	v_and_b32_e32 v5, 0xffff0000, v165
	v_lshlrev_b32_e32 v10, 16, v166
	v_and_b32_e32 v6, 0xffff0000, v166
	v_lshlrev_b32_e32 v11, 16, v167
	v_and_b32_e32 v7, 0xffff0000, v167
	v_mul_f32_e32 v4, 0x3e0293ee, v4
	v_mul_f32_e32 v5, 0x3e0293ee, v5
	v_mul_f32_e32 v6, 0x3e0293ee, v6
	v_mul_f32_e32 v7, 0x3e0293ee, v7
	v_mul_f32_e32 v1, 0x3e0293ee, v1
	v_mul_f32_e32 v3, 0x3e0293ee, v3
	v_mul_f32_e32 v10, 0x3e0293ee, v10
	v_mul_f32_e32 v11, 0x3e0293ee, v11
	v_cvt_pk_bf16_f32 v164, v1, v3
	v_cvt_pk_bf16_f32 v165, v4, v5
	v_cvt_pk_bf16_f32 v166, v10, v6
	v_cvt_pk_bf16_f32 v167, v11, v7
	s_waitcnt vmcnt(5)
; __device__ __forceinline__ float bf2f(unsigned h) { return __uint_as_float(h << 16); }
; __device__ __forceinline__ void na_unit3(char* lds, const bf16_t* __restrict__ Qp, const bf16_t* __restrict__ Knp, const bf16_t* __restrict__ Vp, ...
;     ...
;   for (int d0 = 0; d0 < 8; ++d0) { const u32x4 raw = *reinterpret_cast<const u32x4*>(Qw + d0 * 16); u32x4 w;
; #pragma unroll
;     for (int p = 0; p < 4; ++p) w[p] = cvtpk(bf2f(raw[p] & 0xffffu) * C, bf2f(raw[p] >> 16) * C);
;     qr[d0] = *reinterpret_cast<bf16x8*>(&w); }
;   for (int i = tid; i < 15 * 31; i += NW * 64) tab[i] = rpb_h[i] * 1.4426950408889634f;
	v_lshlrev_b32_e32 v1, 16, v168
	v_and_b32_e32 v3, 0xffff0000, v168
	v_lshlrev_b32_e32 v4, 16, v169
	v_and_b32_e32 v5, 0xffff0000, v169
	v_lshlrev_b32_e32 v10, 16, v170
	v_and_b32_e32 v6, 0xffff0000, v170
	v_lshlrev_b32_e32 v11, 16, v171
	v_and_b32_e32 v7, 0xffff0000, v171
	v_mul_f32_e32 v4, 0x3e0293ee, v4
	v_mul_f32_e32 v5, 0x3e0293ee, v5
	v_mul_f32_e32 v6, 0x3e0293ee, v6
	v_mul_f32_e32 v7, 0x3e0293ee, v7
	v_mul_f32_e32 v1, 0x3e0293ee, v1
	v_mul_f32_e32 v3, 0x3e0293ee, v3
	v_mul_f32_e32 v10, 0x3e0293ee, v10
	v_mul_f32_e32 v11, 0x3e0293ee, v11
	v_cvt_pk_bf16_f32 v168, v1, v3
	v_cvt_pk_bf16_f32 v169, v4, v5
	v_cvt_pk_bf16_f32 v170, v10, v6
	v_cvt_pk_bf16_f32 v171, v11, v7
	s_waitcnt vmcnt(4)
	v_lshlrev_b32_e32 v1, 16, v172
	v_and_b32_e32 v3, 0xffff0000, v172
	v_lshlrev_b32_e32 v4, 16, v173
	v_and_b32_e32 v5, 0xffff0000, v173
	v_lshlrev_b32_e32 v10, 16, v174
	v_and_b32_e32 v6, 0xffff0000, v174
	v_lshlrev_b32_e32 v11, 16, v175
	v_and_b32_e32 v7, 0xffff0000, v175
	v_mul_f32_e32 v4, 0x3e0293ee, v4
	v_mul_f32_e32 v5, 0x3e0293ee, v5
	v_mul_f32_e32 v6, 0x3e0293ee, v6
	v_mul_f32_e32 v7, 0x3e0293ee, v7
	v_mul_f32_e32 v1, 0x3e0293ee, v1
	v_mul_f32_e32 v3, 0x3e0293ee, v3
	v_mul_f32_e32 v10, 0x3e0293ee, v10
	v_mul_f32_e32 v11, 0x3e0293ee, v11
	v_cvt_pk_bf16_f32 v172, v1, v3
	v_cvt_pk_bf16_f32 v173, v4, v5
	v_cvt_pk_bf16_f32 v174, v10, v6
	v_cvt_pk_bf16_f32 v175, v11, v7
	s_waitcnt vmcnt(3)
	v_lshlrev_b32_e32 v1, 16, v176
	v_and_b32_e32 v3, 0xffff0000, v176
	v_lshlrev_b32_e32 v4, 16, v177
	v_and_b32_e32 v5, 0xffff0000, v177
	v_lshlrev_b32_e32 v10, 16, v178
	v_and_b32_e32 v6, 0xffff0000, v178
	v_lshlrev_b32_e32 v11, 16, v179
	v_and_b32_e32 v7, 0xffff0000, v179
	v_mul_f32_e32 v4, 0x3e0293ee, v4
	v_mul_f32_e32 v5, 0x3e0293ee, v5
	v_mul_f32_e32 v6, 0x3e0293ee, v6
	v_mul_f32_e32 v7, 0x3e0293ee, v7
	v_mul_f32_e32 v1, 0x3e0293ee, v1
	v_mul_f32_e32 v3, 0x3e0293ee, v3
	v_mul_f32_e32 v10, 0x3e0293ee, v10
	v_mul_f32_e32 v11, 0x3e0293ee, v11
	v_cvt_pk_bf16_f32 v176, v1, v3
	v_cvt_pk_bf16_f32 v177, v4, v5
	v_cvt_pk_bf16_f32 v178, v10, v6
	v_cvt_pk_bf16_f32 v179, v11, v7
	s_waitcnt vmcnt(2)
	v_lshlrev_b32_e32 v1, 16, v180
	v_and_b32_e32 v3, 0xffff0000, v180
	v_lshlrev_b32_e32 v4, 16, v181
	v_and_b32_e32 v5, 0xffff0000, v181
	v_lshlrev_b32_e32 v10, 16, v182
	v_and_b32_e32 v6, 0xffff0000, v182
	v_lshlrev_b32_e32 v11, 16, v183
	v_and_b32_e32 v7, 0xffff0000, v183
	v_mul_f32_e32 v4, 0x3e0293ee, v4
	v_mul_f32_e32 v5, 0x3e0293ee, v5
	v_mul_f32_e32 v6, 0x3e0293ee, v6
	v_mul_f32_e32 v7, 0x3e0293ee, v7
	v_mul_f32_e32 v1, 0x3e0293ee, v1
	v_mul_f32_e32 v3, 0x3e0293ee, v3
	v_mul_f32_e32 v10, 0x3e0293ee, v10
	v_mul_f32_e32 v11, 0x3e0293ee, v11
	v_cvt_pk_bf16_f32 v180, v1, v3
	v_cvt_pk_bf16_f32 v181, v4, v5
	v_cvt_pk_bf16_f32 v182, v10, v6
	v_cvt_pk_bf16_f32 v183, v11, v7
	s_waitcnt vmcnt(1)
	v_lshlrev_b32_e32 v1, 16, v184
	v_and_b32_e32 v3, 0xffff0000, v184
	v_lshlrev_b32_e32 v4, 16, v185
	v_and_b32_e32 v5, 0xffff0000, v185
	v_lshlrev_b32_e32 v10, 16, v186
	v_and_b32_e32 v6, 0xffff0000, v186
	v_lshlrev_b32_e32 v11, 16, v187
	v_and_b32_e32 v7, 0xffff0000, v187
	v_mul_f32_e32 v4, 0x3e0293ee, v4
	v_mul_f32_e32 v5, 0x3e0293ee, v5
	v_mul_f32_e32 v6, 0x3e0293ee, v6
	v_mul_f32_e32 v7, 0x3e0293ee, v7
	v_mul_f32_e32 v1, 0x3e0293ee, v1
	v_mul_f32_e32 v3, 0x3e0293ee, v3
	v_mul_f32_e32 v10, 0x3e0293ee, v10
	v_mul_f32_e32 v11, 0x3e0293ee, v11
	v_cvt_pk_bf16_f32 v184, v1, v3
	v_cvt_pk_bf16_f32 v185, v4, v5
	v_cvt_pk_bf16_f32 v186, v10, v6
	v_cvt_pk_bf16_f32 v187, v11, v7
	s_waitcnt vmcnt(0)
	v_lshlrev_b32_e32 v1, 16, v188
	v_and_b32_e32 v3, 0xffff0000, v188
	v_lshlrev_b32_e32 v4, 16, v189
	v_and_b32_e32 v5, 0xffff0000, v189
	v_lshlrev_b32_e32 v8, 16, v190
	v_and_b32_e32 v6, 0xffff0000, v190
	v_lshlrev_b32_e32 v9, 16, v191
	v_and_b32_e32 v7, 0xffff0000, v191
	v_mul_f32_e32 v1, 0x3e0293ee, v1
	v_mul_f32_e32 v3, 0x3e0293ee, v3
	v_mul_f32_e32 v4, 0x3e0293ee, v4
	v_mul_f32_e32 v5, 0x3e0293ee, v5
	v_mul_f32_e32 v8, 0x3e0293ee, v8
	v_mul_f32_e32 v6, 0x3e0293ee, v6
	v_mul_f32_e32 v9, 0x3e0293ee, v9
	v_mul_f32_e32 v7, 0x3e0293ee, v7
	v_cvt_pk_bf16_f32 v188, v1, v3
	v_cvt_pk_bf16_f32 v189, v4, v5
	v_cvt_pk_bf16_f32 v190, v8, v6
	v_cvt_pk_bf16_f32 v191, v9, v7
	s_and_saveexec_b64 s[6:7], vcc
	s_cbranch_execz .LBB0_284
	v_max_i32_e32 v1, 0xffffffd1, v2
	v_sub_u32_e32 v1, v1, v2
	v_add_u32_e32 v1, 0x1ff, v1
	s_movk_i32 s5, 0x1ff
	v_cmp_lt_u32_e32 vcc, s5, v1
	s_mov_b64 s[26:27], -1
	v_mov_b32_e32 v4, v2
	s_and_saveexec_b64 s[8:9], vcc
	s_cbranch_execz .LBB0_281
	v_lshrrev_b32_e32 v1, 9, v1
	s_or_b32 s5, s77, s20
	v_readlane_b32 s12, v255, 0
	v_add_u32_e32 v1, 1, v1
	s_mulk_i32 s5, 0x744
	v_readlane_b32 s14, v255, 2
	v_readlane_b32 s15, v255, 3
	s_add_u32 s26, s14, s5
	v_and_b32_e32 v6, 0xfffffe, v1
	v_add_u32_e32 v3, 0x200, v2
	v_readlane_b32 s5, v254, 27
	s_addc_u32 s27, s15, 0
	s_mov_b64 s[36:37], 0
	v_lshl_add_u32 v7, v2, 2, s5
	v_mov_b32_e32 v8, v6
	v_mov_b64_e32 v[4:5], v[2:3]
	v_readlane_b32 s13, v255, 1
	v_readlane_b32 s16, v255, 4
	v_readlane_b32 s17, v255, 5
	v_readlane_b32 s18, v255, 6
	v_readlane_b32 s19, v255, 7
